# v38 + FFN2 down-GEMM epilogue: vmcnt(0) after [load next; store current] relaxed to vmcnt(1) (the store stays in flight)
# speedup vs baseline: 1.0070x; 1.0070x over previous
; __device__ __forceinline__ unsigned pkbf(float lo, float hi) { return pg8::cvt_pk_bf16(lo, hi); }
; __device__ __forceinline__ void unpack8bf(const u32x4 w, float* f) { f[0] = bflo(w.x); f[1] = bfhi(w.x); f[2] = bflo(w.y); f[3] = bfhi(w.y); f[4] = bflo(w.z); f[5] = bfhi(w.z); f[6] = bflo(w.w); f[7] = bfhi(w.w); }
;     __device__ __forceinline__ void operator()(AccRef acc, const Unit& u, int wr, int wc, int fr, int fq) const {
;         asm volatile("" : "+v"(fr), "+v"(fq));
;         const int row0 = u.pm * 256 + wr * 64 + fr, col0 = u.pn * 256 + wc * 32 + 8 * fq;
; #pragma unroll
;         for (int ai = 0; ai < 2; ++ai)
; #pragma unroll
;             for (int m = 0; m < 4; ++m)
; #pragma unroll
;                 for (int bj = 0; bj < 2; ++bj) {
;                     const size_t off = (size_t)(row0 + ai * 128 + m * 16) * DM + col0 + bj * 128;
;                     const u32x4 hw = *(const u32x4*)(Hb + off); float h[8]; unpack8bf(hw, h);
; #pragma unroll
;                     for (int e = 0; e < 4; ++e) { h[e] += 0.5f * acc[ai][bj][m][0][e]; h[4 + e] += 0.5f * acc[ai][bj][m][1][e]; }
;                     u32x4 w; w.x = pkbf(h[0], h[1]); w.y = pkbf(h[2], h[3]); w.z = pkbf(h[4], h[5]); w.w = pkbf(h[6], h[7]);
;                     *(u32x4*)(Hb + off) = w;
;                 }
;     }
.LBB0_1443:
	v_mov_b32_e32 v146, v129
	v_mov_b32_e32 v147, v148
	s_lshl_b32 s14, s77, 8
	s_add_i32 s14, s14, s64
	v_add_u32_e32 v146, s14, v146
	s_lshl_b32 s14, s78, 8
	s_or_b32 s14, s14, s65
	v_lshl_add_u32 v154, v147, 3, s14
	v_ashrrev_i32_e32 v147, 31, v146
	v_lshlrev_b64 v[146:147], 11, v[146:147]
	v_ashrrev_i32_e32 v155, 31, v154
	v_lshl_add_u64 v[146:147], s[30:31], 0, v[146:147]
	v_lshl_add_u64 v[146:147], v[154:155], 1, v[146:147]
	global_load_dwordx4 v[154:157], v[146:147], off
	s_waitcnt vmcnt(0)
	v_lshlrev_b32_e32 v153, 16, v154
	v_and_b32_e32 v154, 0xffff0000, v154
	v_lshlrev_b32_e32 v158, 16, v155
	v_and_b32_e32 v155, 0xffff0000, v155
	v_lshlrev_b32_e32 v159, 16, v156
	v_and_b32_e32 v156, 0xffff0000, v156
	v_lshlrev_b32_e32 v160, 16, v157
	v_and_b32_e32 v157, 0xffff0000, v157
	v_fmac_f32_e32 v153, 0.5, v120
	v_fmac_f32_e32 v159, 0.5, v124
	v_fmac_f32_e32 v154, 0.5, v121
	v_fmac_f32_e32 v156, 0.5, v125
	v_fmac_f32_e32 v158, 0.5, v122
	v_fmac_f32_e32 v160, 0.5, v126
	v_fmac_f32_e32 v155, 0.5, v123
	v_fmac_f32_e32 v157, 0.5, v127
	v_cvt_pk_bf16_f32 v120, v153, v154
	v_cvt_pk_bf16_f32 v121, v158, v155
	v_cvt_pk_bf16_f32 v122, v159, v156
	v_cvt_pk_bf16_f32 v123, v160, v157
	global_load_dwordx4 v[124:127], v[146:147], off offset:256
	v_add_co_u32_e32 v154, vcc, s67, v146
	global_store_dwordx4 v[146:147], v[120:123], off
	s_nop 0
	v_addc_co_u32_e32 v155, vcc, 0, v147, vcc
	s_waitcnt vmcnt(1)
	v_lshlrev_b32_e32 v120, 16, v124
	v_and_b32_e32 v121, 0xffff0000, v124
	v_lshlrev_b32_e32 v122, 16, v125
	v_and_b32_e32 v123, 0xffff0000, v125
	v_lshlrev_b32_e32 v124, 16, v126
	v_and_b32_e32 v125, 0xffff0000, v126
	v_lshlrev_b32_e32 v126, 16, v127
	v_and_b32_e32 v127, 0xffff0000, v127
	v_fmac_f32_e32 v120, 0.5, v116
	v_fmac_f32_e32 v124, 0.5, v112
	v_fmac_f32_e32 v121, 0.5, v117
	v_fmac_f32_e32 v125, 0.5, v113
	v_fmac_f32_e32 v122, 0.5, v118
	v_fmac_f32_e32 v126, 0.5, v114
	v_fmac_f32_e32 v123, 0.5, v119
	v_fmac_f32_e32 v127, 0.5, v115
	v_cvt_pk_bf16_f32 v112, v120, v121
	v_cvt_pk_bf16_f32 v113, v122, v123
	v_cvt_pk_bf16_f32 v114, v124, v125
	v_cvt_pk_bf16_f32 v115, v126, v127
	global_load_dwordx4 v[116:119], v[154:155], off
	v_lshl_add_u64 v[120:121], v[146:147], 0, s[20:21]
	global_store_dwordx4 v[146:147], v[112:115], off offset:256
	s_waitcnt vmcnt(1)
	s_nop 0
	v_lshlrev_b32_e32 v112, 16, v116
	v_and_b32_e32 v113, 0xffff0000, v116
	v_lshlrev_b32_e32 v114, 16, v117
	v_and_b32_e32 v115, 0xffff0000, v117
	v_lshlrev_b32_e32 v116, 16, v118
	v_and_b32_e32 v117, 0xffff0000, v118
	v_lshlrev_b32_e32 v118, 16, v119
	v_and_b32_e32 v119, 0xffff0000, v119
	v_fmac_f32_e32 v112, 0.5, v108
	v_fmac_f32_e32 v116, 0.5, v104
	v_fmac_f32_e32 v113, 0.5, v109
	v_fmac_f32_e32 v117, 0.5, v105
	v_fmac_f32_e32 v114, 0.5, v110
	v_fmac_f32_e32 v118, 0.5, v106
	v_fmac_f32_e32 v115, 0.5, v111
	v_fmac_f32_e32 v119, 0.5, v107
	v_cvt_pk_bf16_f32 v104, v112, v113
	v_cvt_pk_bf16_f32 v105, v114, v115
	v_cvt_pk_bf16_f32 v106, v116, v117
	v_cvt_pk_bf16_f32 v107, v118, v119
	global_load_dwordx4 v[108:111], v[120:121], off offset:256
	v_add_co_u32_e32 v112, vcc, s60, v146
	global_store_dwordx4 v[154:155], v[104:107], off
	s_nop 0
	v_addc_co_u32_e32 v113, vcc, 0, v147, vcc
	s_waitcnt vmcnt(1)
	v_lshlrev_b32_e32 v104, 16, v108
	v_and_b32_e32 v105, 0xffff0000, v108
	v_lshlrev_b32_e32 v106, 16, v109
	v_and_b32_e32 v107, 0xffff0000, v109
	v_lshlrev_b32_e32 v108, 16, v110
	v_and_b32_e32 v109, 0xffff0000, v110
	v_lshlrev_b32_e32 v110, 16, v111
	v_and_b32_e32 v111, 0xffff0000, v111
	v_fmac_f32_e32 v104, 0.5, v100
	v_fmac_f32_e32 v108, 0.5, v96
	v_fmac_f32_e32 v105, 0.5, v101
	v_fmac_f32_e32 v109, 0.5, v97
	v_fmac_f32_e32 v106, 0.5, v102
	v_fmac_f32_e32 v110, 0.5, v98
	v_fmac_f32_e32 v107, 0.5, v103
	v_fmac_f32_e32 v111, 0.5, v99
	v_cvt_pk_bf16_f32 v96, v104, v105
	v_cvt_pk_bf16_f32 v97, v106, v107
	v_cvt_pk_bf16_f32 v98, v108, v109
	v_cvt_pk_bf16_f32 v99, v110, v111
	global_load_dwordx4 v[100:103], v[112:113], off
	v_lshl_add_u64 v[104:105], v[146:147], 0, s[24:25]
	global_store_dwordx4 v[120:121], v[96:99], off offset:256
	s_waitcnt vmcnt(1)
	s_nop 0
	v_lshlrev_b32_e32 v96, 16, v100
	v_and_b32_e32 v97, 0xffff0000, v100
	v_lshlrev_b32_e32 v98, 16, v101
	v_and_b32_e32 v99, 0xffff0000, v101
	v_lshlrev_b32_e32 v100, 16, v102
	v_and_b32_e32 v101, 0xffff0000, v102
	v_lshlrev_b32_e32 v102, 16, v103
	v_and_b32_e32 v103, 0xffff0000, v103
	v_fmac_f32_e32 v96, 0.5, v92
	v_fmac_f32_e32 v100, 0.5, v88
	v_fmac_f32_e32 v97, 0.5, v93
	v_fmac_f32_e32 v101, 0.5, v89
	v_fmac_f32_e32 v98, 0.5, v94
	v_fmac_f32_e32 v102, 0.5, v90
	v_fmac_f32_e32 v99, 0.5, v95
	v_fmac_f32_e32 v103, 0.5, v91
	v_cvt_pk_bf16_f32 v88, v96, v97
	v_cvt_pk_bf16_f32 v89, v98, v99
	v_cvt_pk_bf16_f32 v90, v100, v101
	v_cvt_pk_bf16_f32 v91, v102, v103
	global_load_dwordx4 v[92:95], v[104:105], off offset:256
	v_add_co_u32_e32 v96, vcc, s66, v146
	global_store_dwordx4 v[112:113], v[88:91], off
	s_nop 0
	v_addc_co_u32_e32 v97, vcc, 0, v147, vcc
	s_waitcnt vmcnt(1)
	v_lshlrev_b32_e32 v88, 16, v92
	v_and_b32_e32 v89, 0xffff0000, v92
	v_lshlrev_b32_e32 v90, 16, v93
	v_and_b32_e32 v91, 0xffff0000, v93
	v_lshlrev_b32_e32 v92, 16, v94
	v_and_b32_e32 v93, 0xffff0000, v94
	v_lshlrev_b32_e32 v94, 16, v95
	v_and_b32_e32 v95, 0xffff0000, v95
	v_fmac_f32_e32 v88, 0.5, v84
	v_fmac_f32_e32 v92, 0.5, v80
	v_fmac_f32_e32 v89, 0.5, v85
	v_fmac_f32_e32 v93, 0.5, v81
	v_fmac_f32_e32 v90, 0.5, v86
	v_fmac_f32_e32 v94, 0.5, v82
	v_fmac_f32_e32 v91, 0.5, v87
	v_fmac_f32_e32 v95, 0.5, v83
	v_cvt_pk_bf16_f32 v80, v88, v89
	v_cvt_pk_bf16_f32 v81, v90, v91
	v_cvt_pk_bf16_f32 v82, v92, v93
	v_cvt_pk_bf16_f32 v83, v94, v95
	global_load_dwordx4 v[84:87], v[96:97], off
	v_lshl_add_u64 v[88:89], v[146:147], 0, s[26:27]
	global_store_dwordx4 v[104:105], v[80:83], off offset:256
	s_waitcnt vmcnt(1)
; __device__ __forceinline__ unsigned pkbf(float lo, float hi) { return pg8::cvt_pk_bf16(lo, hi); }
; __device__ __forceinline__ void unpack8bf(const u32x4 w, float* f) { f[0] = bflo(w.x); f[1] = bfhi(w.x); f[2] = bflo(w.y); f[3] = bfhi(w.y); f[4] = bflo(w.z); f[5] = bfhi(w.z); f[6] = bflo(w.w); f[7] = bfhi(w.w); }
;     __device__ __forceinline__ void operator()(AccRef acc, const Unit& u, int wr, int wc, int fr, int fq) const {
;         asm volatile("" : "+v"(fr), "+v"(fq));
;         const int row0 = u.pm * 256 + wr * 64 + fr, col0 = u.pn * 256 + wc * 32 + 8 * fq;
; #pragma unroll
;         for (int ai = 0; ai < 2; ++ai)
; #pragma unroll
;             for (int m = 0; m < 4; ++m)
; #pragma unroll
;                 for (int bj = 0; bj < 2; ++bj) {
;                     const size_t off = (size_t)(row0 + ai * 128 + m * 16) * DM + col0 + bj * 128;
;                     const u32x4 hw = *(const u32x4*)(Hb + off); float h[8]; unpack8bf(hw, h);
; #pragma unroll
;                     for (int e = 0; e < 4; ++e) { h[e] += 0.5f * acc[ai][bj][m][0][e]; h[4 + e] += 0.5f * acc[ai][bj][m][1][e]; }
;                     u32x4 w; w.x = pkbf(h[0], h[1]); w.y = pkbf(h[2], h[3]); w.z = pkbf(h[4], h[5]); w.w = pkbf(h[6], h[7]);
;                     *(u32x4*)(Hb + off) = w;
;                 }
;     }
	s_nop 0
	v_lshlrev_b32_e32 v80, 16, v84
	v_and_b32_e32 v81, 0xffff0000, v84
	v_lshlrev_b32_e32 v82, 16, v85
	v_and_b32_e32 v83, 0xffff0000, v85
	v_lshlrev_b32_e32 v84, 16, v86
	v_and_b32_e32 v85, 0xffff0000, v86
	v_lshlrev_b32_e32 v86, 16, v87
	v_and_b32_e32 v87, 0xffff0000, v87
	v_fmac_f32_e32 v80, 0.5, v76
	v_fmac_f32_e32 v84, 0.5, v72
	v_fmac_f32_e32 v81, 0.5, v77
	v_fmac_f32_e32 v85, 0.5, v73
	v_fmac_f32_e32 v82, 0.5, v78
	v_fmac_f32_e32 v86, 0.5, v74
	v_fmac_f32_e32 v83, 0.5, v79
	v_fmac_f32_e32 v87, 0.5, v75
	v_cvt_pk_bf16_f32 v72, v80, v81
	v_cvt_pk_bf16_f32 v73, v82, v83
	v_cvt_pk_bf16_f32 v74, v84, v85
	v_cvt_pk_bf16_f32 v75, v86, v87
	global_load_dwordx4 v[76:79], v[88:89], off offset:256
	v_add_co_u32_e32 v80, vcc, s71, v146
	global_store_dwordx4 v[96:97], v[72:75], off
	s_nop 0
	v_addc_co_u32_e32 v81, vcc, 0, v147, vcc
	s_waitcnt vmcnt(1)
	v_lshlrev_b32_e32 v72, 16, v76
	v_and_b32_e32 v73, 0xffff0000, v76
	v_lshlrev_b32_e32 v74, 16, v77
	v_and_b32_e32 v75, 0xffff0000, v77
	v_lshlrev_b32_e32 v76, 16, v78
	v_and_b32_e32 v77, 0xffff0000, v78
	v_lshlrev_b32_e32 v78, 16, v79
	v_and_b32_e32 v79, 0xffff0000, v79
	v_fmac_f32_e32 v72, 0.5, v68
	v_fmac_f32_e32 v76, 0.5, v64
	v_fmac_f32_e32 v73, 0.5, v69
	v_fmac_f32_e32 v77, 0.5, v65
	v_fmac_f32_e32 v74, 0.5, v70
	v_fmac_f32_e32 v78, 0.5, v66
	v_fmac_f32_e32 v75, 0.5, v71
	v_fmac_f32_e32 v79, 0.5, v67
	v_cvt_pk_bf16_f32 v64, v72, v73
	v_cvt_pk_bf16_f32 v65, v74, v75
	v_cvt_pk_bf16_f32 v66, v76, v77
	v_cvt_pk_bf16_f32 v67, v78, v79
	global_load_dwordx4 v[68:71], v[80:81], off
	v_lshl_add_u64 v[72:73], v[146:147], 0, s[28:29]
	global_store_dwordx4 v[88:89], v[64:67], off offset:256
	s_waitcnt vmcnt(1)
	s_nop 0
	v_lshlrev_b32_e32 v64, 16, v68
	v_and_b32_e32 v65, 0xffff0000, v68
	v_lshlrev_b32_e32 v66, 16, v69
	v_and_b32_e32 v67, 0xffff0000, v69
	v_lshlrev_b32_e32 v68, 16, v70
	v_and_b32_e32 v69, 0xffff0000, v70
	v_lshlrev_b32_e32 v70, 16, v71
	v_and_b32_e32 v71, 0xffff0000, v71
	v_fmac_f32_e32 v64, 0.5, v60
	v_fmac_f32_e32 v68, 0.5, v56
	v_fmac_f32_e32 v65, 0.5, v61
	v_fmac_f32_e32 v69, 0.5, v57
	v_fmac_f32_e32 v66, 0.5, v62
	v_fmac_f32_e32 v70, 0.5, v58
	v_fmac_f32_e32 v67, 0.5, v63
	v_fmac_f32_e32 v71, 0.5, v59
	v_cvt_pk_bf16_f32 v56, v64, v65
	v_cvt_pk_bf16_f32 v57, v66, v67
	v_cvt_pk_bf16_f32 v58, v68, v69
	v_cvt_pk_bf16_f32 v59, v70, v71
	global_load_dwordx4 v[60:63], v[72:73], off offset:256
	v_add_co_u32_e32 v64, vcc, s72, v146
	global_store_dwordx4 v[80:81], v[56:59], off
	s_nop 0
	v_addc_co_u32_e32 v65, vcc, 0, v147, vcc
	s_waitcnt vmcnt(1)
	v_lshlrev_b32_e32 v56, 16, v60
	v_and_b32_e32 v57, 0xffff0000, v60
	v_lshlrev_b32_e32 v58, 16, v61
	v_and_b32_e32 v59, 0xffff0000, v61
	v_lshlrev_b32_e32 v60, 16, v62
	v_and_b32_e32 v61, 0xffff0000, v62
	v_lshlrev_b32_e32 v62, 16, v63
	v_and_b32_e32 v63, 0xffff0000, v63
	v_fmac_f32_e32 v56, 0.5, v52
	v_fmac_f32_e32 v60, 0.5, v48
	v_fmac_f32_e32 v57, 0.5, v53
	v_fmac_f32_e32 v61, 0.5, v49
	v_fmac_f32_e32 v58, 0.5, v54
	v_fmac_f32_e32 v62, 0.5, v50
	v_fmac_f32_e32 v59, 0.5, v55
	v_fmac_f32_e32 v63, 0.5, v51
	v_cvt_pk_bf16_f32 v48, v56, v57
	v_cvt_pk_bf16_f32 v49, v58, v59
	v_cvt_pk_bf16_f32 v50, v60, v61
	v_cvt_pk_bf16_f32 v51, v62, v63
	global_load_dwordx4 v[52:55], v[64:65], off
	v_lshl_add_u64 v[56:57], v[146:147], 0, s[36:37]
	global_store_dwordx4 v[72:73], v[48:51], off offset:256
	s_waitcnt vmcnt(1)
	s_nop 0
	v_lshlrev_b32_e32 v48, 16, v52
	v_and_b32_e32 v49, 0xffff0000, v52
	v_lshlrev_b32_e32 v50, 16, v53
	v_and_b32_e32 v51, 0xffff0000, v53
	v_lshlrev_b32_e32 v52, 16, v54
	v_and_b32_e32 v53, 0xffff0000, v54
	v_lshlrev_b32_e32 v54, 16, v55
	v_and_b32_e32 v55, 0xffff0000, v55
	v_fmac_f32_e32 v48, 0.5, v44
	v_fmac_f32_e32 v52, 0.5, v40
	v_fmac_f32_e32 v49, 0.5, v45
	v_fmac_f32_e32 v53, 0.5, v41
	v_fmac_f32_e32 v50, 0.5, v46
	v_fmac_f32_e32 v54, 0.5, v42
	v_fmac_f32_e32 v51, 0.5, v47
	v_fmac_f32_e32 v55, 0.5, v43
	v_cvt_pk_bf16_f32 v40, v48, v49
	v_cvt_pk_bf16_f32 v41, v50, v51
	v_cvt_pk_bf16_f32 v42, v52, v53
	v_cvt_pk_bf16_f32 v43, v54, v55
	global_load_dwordx4 v[44:47], v[56:57], off offset:256
	v_add_co_u32_e32 v48, vcc, s73, v146
	global_store_dwordx4 v[64:65], v[40:43], off
	s_nop 0
	v_addc_co_u32_e32 v49, vcc, 0, v147, vcc
	s_waitcnt vmcnt(1)
; #define PG8_BAR __builtin_amdgcn_s_barrier()
; __device__ __forceinline__ unsigned pkbf(float lo, float hi) { return pg8::cvt_pk_bf16(lo, hi); }
; __device__ __forceinline__ void unpack8bf(const u32x4 w, float* f) { f[0] = bflo(w.x); f[1] = bfhi(w.x); f[2] = bflo(w.y); f[3] = bfhi(w.y); f[4] = bflo(w.z); f[5] = bfhi(w.z); f[6] = bflo(w.w); f[7] = bfhi(w.w); }
; template <class Epi, class Sched, bool ALIGN_EPI = false, bool SP2 = false>
; __device__ __forceinline__ void gemm_phase(PG8_LAS unsigned char* lds, const Gemm g, const Sched& S, const Epi& E) {
;     ...
;         if (!has_next) break;
; #pragma unroll
;         for (int a = 0; a < 2; ++a)
; #pragma unroll
;             for (int b = 0; b < 2; ++b)
; #pragma unroll
;                 for (int m = 0; m < 4; ++m)
; #pragma unroll
;                     for (int n = 0; n < 2; ++n) acc[a][b][m][n] = (f32x4){0.f, 0.f, 0.f, 0.f};
;         cur = nxt; cA = nA; cB = nB; ++ui;
;         if constexpr (ALIGN_EPI) { if (wr == 1) PG8_BAR; }
;     __device__ __forceinline__ void operator()(AccRef acc, const Unit& u, int wr, int wc, int fr, int fq) const {
;         asm volatile("" : "+v"(fr), "+v"(fq));
;         const int row0 = u.pm * 256 + wr * 64 + fr, col0 = u.pn * 256 + wc * 32 + 8 * fq;
; #pragma unroll
;         for (int ai = 0; ai < 2; ++ai)
; #pragma unroll
;             for (int m = 0; m < 4; ++m)
; #pragma unroll
;                 for (int bj = 0; bj < 2; ++bj) {
;                     const size_t off = (size_t)(row0 + ai * 128 + m * 16) * DM + col0 + bj * 128;
;                     const u32x4 hw = *(const u32x4*)(Hb + off); float h[8]; unpack8bf(hw, h);
; #pragma unroll
;                     for (int e = 0; e < 4; ++e) { h[e] += 0.5f * acc[ai][bj][m][0][e]; h[4 + e] += 0.5f * acc[ai][bj][m][1][e]; }
;                     u32x4 w; w.x = pkbf(h[0], h[1]); w.y = pkbf(h[2], h[3]); w.z = pkbf(h[4], h[5]); w.w = pkbf(h[6], h[7]);
;                     *(u32x4*)(Hb + off) = w;
;                 }
;     }
	v_lshlrev_b32_e32 v40, 16, v44
	v_and_b32_e32 v41, 0xffff0000, v44
	v_lshlrev_b32_e32 v42, 16, v45
	v_and_b32_e32 v43, 0xffff0000, v45
	v_lshlrev_b32_e32 v44, 16, v46
	v_and_b32_e32 v45, 0xffff0000, v46
	v_lshlrev_b32_e32 v46, 16, v47
	v_and_b32_e32 v47, 0xffff0000, v47
	v_fmac_f32_e32 v40, 0.5, v36
	v_fmac_f32_e32 v44, 0.5, v32
	v_fmac_f32_e32 v41, 0.5, v37
	v_fmac_f32_e32 v45, 0.5, v33
	v_fmac_f32_e32 v42, 0.5, v38
	v_fmac_f32_e32 v46, 0.5, v34
	v_fmac_f32_e32 v43, 0.5, v39
	v_fmac_f32_e32 v47, 0.5, v35
	v_cvt_pk_bf16_f32 v32, v40, v41
	v_cvt_pk_bf16_f32 v33, v42, v43
	v_cvt_pk_bf16_f32 v34, v44, v45
	v_cvt_pk_bf16_f32 v35, v46, v47
	global_load_dwordx4 v[36:39], v[48:49], off
	v_lshl_add_u64 v[40:41], v[146:147], 0, s[38:39]
	global_store_dwordx4 v[56:57], v[32:35], off offset:256
	s_waitcnt vmcnt(1)
	s_nop 0
	v_lshlrev_b32_e32 v32, 16, v36
	v_and_b32_e32 v33, 0xffff0000, v36
	v_lshlrev_b32_e32 v34, 16, v37
	v_and_b32_e32 v35, 0xffff0000, v37
	v_lshlrev_b32_e32 v36, 16, v38
	v_and_b32_e32 v37, 0xffff0000, v38
	v_lshlrev_b32_e32 v38, 16, v39
	v_and_b32_e32 v39, 0xffff0000, v39
	v_fmac_f32_e32 v32, 0.5, v28
	v_fmac_f32_e32 v36, 0.5, v24
	v_fmac_f32_e32 v33, 0.5, v29
	v_fmac_f32_e32 v37, 0.5, v25
	v_fmac_f32_e32 v34, 0.5, v30
	v_fmac_f32_e32 v38, 0.5, v26
	v_fmac_f32_e32 v35, 0.5, v31
	v_fmac_f32_e32 v39, 0.5, v27
	v_cvt_pk_bf16_f32 v24, v32, v33
	v_cvt_pk_bf16_f32 v25, v34, v35
	v_cvt_pk_bf16_f32 v26, v36, v37
	v_cvt_pk_bf16_f32 v27, v38, v39
	global_load_dwordx4 v[28:31], v[40:41], off offset:256
	v_add_co_u32_e32 v32, vcc, s74, v146
	global_store_dwordx4 v[48:49], v[24:27], off
	s_nop 0
	v_addc_co_u32_e32 v33, vcc, 0, v147, vcc
	s_and_b64 vcc, exec, s[4:5]
	s_mov_b64 s[4:5], -1
	s_waitcnt vmcnt(1)
	v_lshlrev_b32_e32 v24, 16, v28
	v_and_b32_e32 v25, 0xffff0000, v28
	v_lshlrev_b32_e32 v26, 16, v29
	v_and_b32_e32 v27, 0xffff0000, v29
	v_lshlrev_b32_e32 v28, 16, v30
	v_and_b32_e32 v29, 0xffff0000, v30
	v_lshlrev_b32_e32 v30, 16, v31
	v_and_b32_e32 v31, 0xffff0000, v31
	v_fmac_f32_e32 v24, 0.5, v20
	v_fmac_f32_e32 v28, 0.5, v16
	v_fmac_f32_e32 v25, 0.5, v21
	v_fmac_f32_e32 v29, 0.5, v17
	v_fmac_f32_e32 v26, 0.5, v22
	v_fmac_f32_e32 v30, 0.5, v18
	v_fmac_f32_e32 v27, 0.5, v23
	v_fmac_f32_e32 v31, 0.5, v19
	v_cvt_pk_bf16_f32 v16, v24, v25
	v_cvt_pk_bf16_f32 v17, v26, v27
	v_cvt_pk_bf16_f32 v18, v28, v29
	v_cvt_pk_bf16_f32 v19, v30, v31
	global_load_dwordx4 v[20:23], v[32:33], off
	v_lshl_add_u64 v[24:25], v[146:147], 0, s[40:41]
	global_store_dwordx4 v[40:41], v[16:19], off offset:256
	s_waitcnt vmcnt(1)
	s_nop 0
	v_lshlrev_b32_e32 v16, 16, v20
	v_and_b32_e32 v17, 0xffff0000, v20
	v_lshlrev_b32_e32 v18, 16, v21
	v_and_b32_e32 v19, 0xffff0000, v21
	v_lshlrev_b32_e32 v20, 16, v22
	v_and_b32_e32 v21, 0xffff0000, v22
	v_lshlrev_b32_e32 v22, 16, v23
	v_and_b32_e32 v23, 0xffff0000, v23
	v_fmac_f32_e32 v16, 0.5, v12
	v_fmac_f32_e32 v20, 0.5, v8
	v_fmac_f32_e32 v17, 0.5, v13
	v_fmac_f32_e32 v21, 0.5, v9
	v_fmac_f32_e32 v18, 0.5, v14
	v_fmac_f32_e32 v22, 0.5, v10
	v_fmac_f32_e32 v19, 0.5, v15
	v_fmac_f32_e32 v23, 0.5, v11
	v_cvt_pk_bf16_f32 v8, v16, v17
	v_cvt_pk_bf16_f32 v9, v18, v19
	v_cvt_pk_bf16_f32 v10, v20, v21
	v_cvt_pk_bf16_f32 v11, v22, v23
	global_load_dwordx4 v[12:15], v[24:25], off offset:256
	s_nop 0
	global_store_dwordx4 v[32:33], v[8:11], off
	s_waitcnt vmcnt(1)
	s_nop 0
	v_lshlrev_b32_e32 v8, 16, v12
	v_and_b32_e32 v9, 0xffff0000, v12
	v_lshlrev_b32_e32 v10, 16, v13
	v_and_b32_e32 v11, 0xffff0000, v13
	v_lshlrev_b32_e32 v12, 16, v14
	v_and_b32_e32 v13, 0xffff0000, v14
	v_lshlrev_b32_e32 v14, 16, v15
	v_and_b32_e32 v15, 0xffff0000, v15
	v_fmac_f32_e32 v8, 0.5, v4
	v_fmac_f32_e32 v12, 0.5, v0
	v_fmac_f32_e32 v9, 0.5, v5
	v_fmac_f32_e32 v13, 0.5, v1
	v_fmac_f32_e32 v10, 0.5, v6
	v_fmac_f32_e32 v14, 0.5, v2
	v_fmac_f32_e32 v11, 0.5, v7
	v_fmac_f32_e32 v15, 0.5, v3
	v_cvt_pk_bf16_f32 v0, v8, v9
	v_cvt_pk_bf16_f32 v1, v10, v11
	v_cvt_pk_bf16_f32 v2, v12, v13
	v_cvt_pk_bf16_f32 v3, v14, v15
	global_store_dwordx4 v[24:25], v[0:3], off offset:256
	s_cbranch_vccnz .LBB0_1431
	s_andn2_b64 vcc, exec, s[10:11]
	s_cbranch_vccnz .LBB0_1430
	s_barrier
	s_branch .LBB0_1430
